# attention P.V: counted lgkmcnt waits per MFMA (wait only for the two transposed reads that MFMA consumes)
# speedup vs baseline: 1.0054x; 1.0006x over previous
.LBB0_215:
	v_lshl_add_u64 v[150:151], v[148:149], 0, s[58:59]
	ds_read_b128 v[64:67], v181 offset:49152
	ds_read_b128 v[68:71], v181 offset:57344
	v_add_f32_e32 v128, 0, v234
	v_add_f32_e32 v128, v235, v128
	v_add_f32_e32 v128, v236, v128
	s_waitcnt lgkmcnt(1)
	v_mfma_f32_32x32x16_bf16 v[80:95], v[64:67], v[108:111], 0
	v_add_f32_e32 v128, v237, v128
	v_add_f32_e32 v128, v238, v128
	ds_read_b128 v[202:205], v182 offset:49152
	ds_read_b128 v[206:209], v182 offset:57344
	v_add_f32_e32 v128, v239, v128
	v_add_f32_e32 v128, v240, v128
	v_add_f32_e32 v128, v241, v128
	v_add_f32_e32 v128, v242, v128
	s_waitcnt lgkmcnt(2)
	v_mfma_f32_32x32x16_bf16 v[64:79], v[68:71], v[108:111], 0
	v_add_f32_e32 v128, v243, v128
	v_add_f32_e32 v128, v244, v128
	v_add_f32_e32 v128, v245, v128
	v_add_f32_e32 v128, v246, v128
	v_add_f32_e32 v128, v247, v128
	v_add_f32_e32 v128, v252, v128
	v_add_f32_e32 v128, v253, v128
	s_waitcnt lgkmcnt(1)
	v_mfma_f32_32x32x16_bf16 v[80:95], v[202:205], v[104:107], v[80:95]
	v_add_f32_e32 v128, v218, v128
	v_add_f32_e32 v128, v219, v128
	v_add_f32_e32 v128, v220, v128
	v_add_f32_e32 v128, v221, v128
	v_add_f32_e32 v128, v222, v128
	v_add_f32_e32 v128, v223, v128
	v_add_f32_e32 v128, v224, v128
	s_waitcnt lgkmcnt(0)
	v_mfma_f32_32x32x16_bf16 v[64:79], v[206:209], v[104:107], v[64:79]
	ds_read_b128 v[202:205], v183 offset:49152
	ds_read_b128 v[206:209], v183 offset:57344
	v_add_f32_e32 v128, v225, v128
	v_add_f32_e32 v128, v226, v128
	v_add_f32_e32 v128, v227, v128
	v_add_f32_e32 v128, v228, v128
	v_add_f32_e32 v128, v229, v128
	v_add_f32_e32 v128, v230, v128
	s_waitcnt lgkmcnt(1)
	v_mfma_f32_32x32x16_bf16 v[80:95], v[202:205], v[100:103], v[80:95]
	v_add_f32_e32 v128, v231, v128
	v_add_f32_e32 v128, v232, v128
	v_add_f32_e32 v187, v233, v128
	v_mov_b32_e32 v188, v187
	v_lshl_add_u64 v[152:153], v[146:147], 0, s[58:59]
	s_nop 0
	v_permlane32_swap_b32_e32 v187, v188
	s_waitcnt lgkmcnt(0)
	v_mfma_f32_32x32x16_bf16 v[64:79], v[206:209], v[100:103], v[64:79]
	ds_read_b128 v[202:205], v184 offset:49152
	ds_read_b128 v[206:209], v184 offset:57344
	v_cvt_pk_bf16_f32 v128, v234, v235
	v_cvt_pk_bf16_f32 v129, v236, v237
	v_cvt_pk_bf16_f32 v130, v238, v239
	v_cvt_pk_bf16_f32 v131, v240, v241
	v_cvt_pk_bf16_f32 v198, v242, v243
	v_cvt_pk_bf16_f32 v199, v244, v245
	s_waitcnt lgkmcnt(1)
	v_mfma_f32_32x32x16_bf16 v[80:95], v[202:205], v[96:99], v[80:95]
	v_permlane32_swap_b32_e32 v128, v130
	v_cvt_pk_bf16_f32 v200, v246, v247
	v_cvt_pk_bf16_f32 v201, v252, v253
	v_cvt_pk_bf16_f32 v190, v218, v219
	v_cvt_pk_bf16_f32 v191, v220, v221
	v_cvt_pk_bf16_f32 v192, v222, v223
	s_waitcnt lgkmcnt(0)
	v_mfma_f32_32x32x16_bf16 v[64:79], v[206:209], v[96:99], v[64:79]
	v_add_co_u32_e32 v116, vcc, s86, v152
	s_nop 1
	v_addc_co_u32_e32 v117, vcc, 0, v153, vcc
	v_add_co_u32_e32 v120, vcc, s86, v150
	s_nop 1
	v_addc_co_u32_e32 v121, vcc, 0, v151, vcc
	ds_read_b64_tr_b16 v[202:203], v177 offset:0
	ds_read_b64_tr_b16 v[204:205], v177 offset:0x800
	ds_read_b64_tr_b16 v[206:207], v177 offset:0x1000
	ds_read_b64_tr_b16 v[208:209], v177 offset:0x1800
	ds_read_b64_tr_b16 v[210:211], v177 offset:0x2000
	ds_read_b64_tr_b16 v[212:213], v177 offset:0x2800
	ds_read_b64_tr_b16 v[214:215], v177 offset:0x3000
	ds_read_b64_tr_b16 v[216:217], v177 offset:0x3800
	v_cvt_pk_bf16_f32 v193, v224, v225
	v_cvt_pk_bf16_f32 v194, v226, v227
	v_cvt_pk_bf16_f32 v195, v228, v229
	v_cvt_pk_bf16_f32 v196, v230, v231
	v_cvt_pk_bf16_f32 v197, v232, v233
	v_permlane32_swap_b32_e32 v129, v131
	v_permlane32_swap_b32_e32 v198, v200
	v_permlane32_swap_b32_e32 v199, v201
	v_permlane32_swap_b32_e32 v190, v192
	v_permlane32_swap_b32_e32 v191, v193
	v_permlane32_swap_b32_e32 v194, v196
	v_permlane32_swap_b32_e32 v195, v197
	global_load_dwordx4 v[112:115], v[116:117], off offset:1024
	s_nop 0
	global_load_dwordx4 v[116:119], v[116:117], off
	s_nop 0
	global_load_dwordx4 v[124:127], v[120:121], off offset:1024
	s_nop 0
	global_load_dwordx4 v[120:123], v[120:121], off
	s_nop 0
	s_waitcnt lgkmcnt(6)
	v_mfma_f32_32x32x16_bf16 v[0:15], v[128:131], v[202:205], v[0:15]
	ds_read_b64_tr_b16 v[202:203], v177 offset:0x200
	ds_read_b64_tr_b16 v[204:205], v177 offset:0xa00
	v_max_f32_e32 v250, v80, v81
	v_max3_f32 v250, v250, v82, v83
	v_max3_f32 v250, v250, v84, v85
	v_max3_f32 v250, v250, v86, v87
	v_max3_f32 v250, v250, v88, v89
	v_max3_f32 v250, v250, v90, v91
	v_max3_f32 v250, v250, v92, v93
	s_waitcnt lgkmcnt(6)
	v_mfma_f32_32x32x16_bf16 v[0:15], v[198:201], v[206:209], v[0:15]
	ds_read_b64_tr_b16 v[206:207], v177 offset:0x1200
	ds_read_b64_tr_b16 v[208:209], v177 offset:0x1a00
	v_max3_f32 v250, v250, v94, v95
	v_max3_f32 v250, v250, v64, v65
	v_max3_f32 v250, v250, v66, v67
	v_max3_f32 v250, v250, v68, v69
	v_max3_f32 v250, v250, v70, v71
	v_max3_f32 v250, v250, v72, v73
	v_max3_f32 v250, v250, v74, v75
	v_max3_f32 v250, v250, v76, v77
	v_max3_f32 v250, v250, v78, v79
	s_waitcnt lgkmcnt(6)
	v_mfma_f32_32x32x16_bf16 v[0:15], v[190:193], v[210:213], v[0:15]
	ds_read_b64_tr_b16 v[210:211], v177 offset:0x2200
	ds_read_b64_tr_b16 v[212:213], v177 offset:0x2a00
	v_mov_b32_e32 v251, v250
	s_nop 1
	v_permlane32_swap_b32_e32 v250, v251
	v_max_f32_e32 v250, v250, v251
	v_sub_f32_e32 v251, v250, v186
	v_cmp_ge_f32_e32 vcc, s33, v251
	v_max_f32_e32 v251, v186, v186
	v_max_f32_e32 v250, v251, v250
	s_waitcnt lgkmcnt(6)
	v_mfma_f32_32x32x16_bf16 v[0:15], v[194:197], v[214:217], v[0:15]
	ds_read_b64_tr_b16 v[214:215], v177 offset:0x3200
	ds_read_b64_tr_b16 v[216:217], v177 offset:0x3a00
	v_sub_f32_e32 v251, v186, v250
	v_mul_f32_e32 v251, 0x3e38aa3b, v251
	v_exp_f32_e32 v251, v251
	s_cmp_eq_u64 vcc, exec
	s_cselect_b64 s[6:7], -1, 0
	v_cndmask_b32_e64 v186, v250, v186, s[6:7]
	v_mul_f32_e32 v254, 0xbe38aa3b, v186
	s_waitcnt lgkmcnt(6)
	v_mfma_f32_32x32x16_bf16 v[48:63], v[128:131], v[202:205], v[48:63]
	ds_read_b64_tr_b16 v[202:203], v177 offset:0x400
	ds_read_b64_tr_b16 v[204:205], v177 offset:0xc00
	v_fmamk_f32 v80, v80, 0x3e38aa3b, v254
	v_fmamk_f32 v81, v81, 0x3e38aa3b, v254
	v_fmamk_f32 v64, v64, 0x3e38aa3b, v254
	v_fmamk_f32 v65, v65, 0x3e38aa3b, v254
	v_exp_f32_e32 v234, v80
	v_exp_f32_e32 v235, v81
	v_fmamk_f32 v82, v82, 0x3e38aa3b, v254
	v_fmamk_f32 v83, v83, 0x3e38aa3b, v254
	s_waitcnt lgkmcnt(6)
	v_mfma_f32_32x32x16_bf16 v[48:63], v[198:201], v[206:209], v[48:63]
	ds_read_b64_tr_b16 v[206:207], v177 offset:0x1400
	ds_read_b64_tr_b16 v[208:209], v177 offset:0x1c00
	v_exp_f32_e32 v218, v64
	v_exp_f32_e32 v219, v65
	v_fmamk_f32 v66, v66, 0x3e38aa3b, v254
	v_fmamk_f32 v67, v67, 0x3e38aa3b, v254
	v_exp_f32_e32 v236, v82
	s_waitcnt lgkmcnt(6)
	v_mfma_f32_32x32x16_bf16 v[48:63], v[190:193], v[210:213], v[48:63]
	ds_read_b64_tr_b16 v[210:211], v177 offset:0x2400
	ds_read_b64_tr_b16 v[212:213], v177 offset:0x2c00
	v_exp_f32_e32 v237, v83
	v_fmamk_f32 v84, v84, 0x3e38aa3b, v254
	v_fmamk_f32 v85, v85, 0x3e38aa3b, v254
	v_exp_f32_e32 v220, v66
	v_exp_f32_e32 v221, v67
	s_waitcnt lgkmcnt(6)
	v_mfma_f32_32x32x16_bf16 v[48:63], v[194:197], v[214:217], v[48:63]
	ds_read_b64_tr_b16 v[214:215], v177 offset:0x3400
	ds_read_b64_tr_b16 v[216:217], v177 offset:0x3c00
	v_fmamk_f32 v68, v68, 0x3e38aa3b, v254
	v_fmamk_f32 v69, v69, 0x3e38aa3b, v254
	v_exp_f32_e32 v238, v84
	v_exp_f32_e32 v239, v85
	v_fmamk_f32 v86, v86, 0x3e38aa3b, v254
	v_fmamk_f32 v87, v87, 0x3e38aa3b, v254
	s_waitcnt lgkmcnt(6)
	v_mfma_f32_32x32x16_bf16 v[32:47], v[128:131], v[202:205], v[32:47]
	ds_read_b64_tr_b16 v[202:203], v177 offset:0x600
	ds_read_b64_tr_b16 v[204:205], v177 offset:0xe00
	v_exp_f32_e32 v222, v68
	v_exp_f32_e32 v223, v69
	v_fmamk_f32 v70, v70, 0x3e38aa3b, v254
	v_fmamk_f32 v71, v71, 0x3e38aa3b, v254
	v_exp_f32_e32 v240, v86
	s_waitcnt lgkmcnt(6)
	v_mfma_f32_32x32x16_bf16 v[32:47], v[198:201], v[206:209], v[32:47]
	ds_read_b64_tr_b16 v[206:207], v177 offset:0x1600
	ds_read_b64_tr_b16 v[208:209], v177 offset:0x1e00
	v_exp_f32_e32 v241, v87
	v_fmamk_f32 v88, v88, 0x3e38aa3b, v254
	v_fmamk_f32 v89, v89, 0x3e38aa3b, v254
	v_exp_f32_e32 v224, v70
	v_exp_f32_e32 v225, v71
	s_waitcnt lgkmcnt(6)
	v_mfma_f32_32x32x16_bf16 v[32:47], v[190:193], v[210:213], v[32:47]
	ds_read_b64_tr_b16 v[210:211], v177 offset:0x2600
	ds_read_b64_tr_b16 v[212:213], v177 offset:0x2e00
	v_fmamk_f32 v72, v72, 0x3e38aa3b, v254
	v_fmamk_f32 v73, v73, 0x3e38aa3b, v254
	v_exp_f32_e32 v242, v88
	v_exp_f32_e32 v243, v89
	v_fmamk_f32 v90, v90, 0x3e38aa3b, v254
	v_fmamk_f32 v91, v91, 0x3e38aa3b, v254
	s_waitcnt lgkmcnt(6)
	v_mfma_f32_32x32x16_bf16 v[32:47], v[194:197], v[214:217], v[32:47]
	ds_read_b64_tr_b16 v[214:215], v177 offset:0x3600
	ds_read_b64_tr_b16 v[216:217], v177 offset:0x3e00
	v_exp_f32_e32 v226, v72
	v_exp_f32_e32 v227, v73
	v_fmamk_f32 v74, v74, 0x3e38aa3b, v254
	v_fmamk_f32 v75, v75, 0x3e38aa3b, v254
	v_exp_f32_e32 v244, v90
	s_waitcnt lgkmcnt(6)
	v_mfma_f32_32x32x16_bf16 v[16:31], v[128:131], v[202:205], v[16:31]
	v_exp_f32_e32 v245, v91
	v_fmamk_f32 v92, v92, 0x3e38aa3b, v254
	v_fmamk_f32 v93, v93, 0x3e38aa3b, v254
	v_exp_f32_e32 v228, v74
	v_exp_f32_e32 v229, v75
	s_waitcnt lgkmcnt(4)
	v_mfma_f32_32x32x16_bf16 v[16:31], v[198:201], v[206:209], v[16:31]
	v_fmamk_f32 v76, v76, 0x3e38aa3b, v254
	v_fmamk_f32 v77, v77, 0x3e38aa3b, v254
	v_exp_f32_e32 v246, v92
	v_exp_f32_e32 v247, v93
	v_fmamk_f32 v94, v94, 0x3e38aa3b, v254
	v_fmamk_f32 v95, v95, 0x3e38aa3b, v254
	s_waitcnt lgkmcnt(2)
	v_mfma_f32_32x32x16_bf16 v[16:31], v[190:193], v[210:213], v[16:31]
	v_exp_f32_e32 v230, v76
	v_exp_f32_e32 v231, v77
	v_fmamk_f32 v78, v78, 0x3e38aa3b, v254
	v_fmamk_f32 v79, v79, 0x3e38aa3b, v254
	v_exp_f32_e32 v252, v94
	s_waitcnt lgkmcnt(0)
	v_mfma_f32_32x32x16_bf16 v[16:31], v[194:197], v[214:217], v[16:31]
	v_exp_f32_e32 v253, v95
	s_nop 0
	v_exp_f32_e32 v232, v78
	v_exp_f32_e32 v233, v79
	s_barrier
	s_waitcnt vmcnt(0)
	v_cndmask_b32_e64 v202, v251, 1.0, s[6:7]
	v_cmp_gt_f32_e32 vcc, 1.0, v202
	s_waitcnt vmcnt(3)
	ds_write_b128 v134, v[112:115]
	s_waitcnt vmcnt(1)
	ds_write_b128 v145, v[124:127]
	ds_write_b128 v175, v[116:119] offset:32768
	s_waitcnt vmcnt(0)
	ds_write_b128 v180, v[120:123] offset:32768
	s_cbranch_vccz .LBB0_219
	s_and_saveexec_b64 s[60:61], s[4:5]
	ds_write_b32 v176, v202 offset:128
	s_or_b64 exec, exec, s[60:61]
	s_waitcnt lgkmcnt(0)
	v_add_u32_e32 v124, v174, v144
	ds_read_b128 v[112:115], v124 offset:224
	ds_read_b128 v[116:119], v124 offset:192
	ds_read_b128 v[120:123], v124 offset:160
	ds_read_b128 v[124:127], v124 offset:128
	s_waitcnt lgkmcnt(3)
	v_pk_mul_f32 v[12:13], v[12:13], v[112:113]
	s_waitcnt lgkmcnt(2)
	v_pk_mul_f32 v[8:9], v[8:9], v[116:117]
	s_waitcnt lgkmcnt(1)
	v_pk_mul_f32 v[4:5], v[4:5], v[120:121]
	v_pk_mul_f32 v[14:15], v[14:15], v[114:115]
	v_pk_mul_f32 v[10:11], v[10:11], v[118:119]
	v_pk_mul_f32 v[6:7], v[6:7], v[122:123]
	s_waitcnt lgkmcnt(0)
	v_pk_mul_f32 v[2:3], v[2:3], v[126:127]
	v_pk_mul_f32 v[0:1], v[0:1], v[124:125]
	v_pk_mul_f32 v[60:61], v[60:61], v[112:113]
	v_pk_mul_f32 v[56:57], v[56:57], v[116:117]
	v_pk_mul_f32 v[52:53], v[52:53], v[120:121]
	v_pk_mul_f32 v[62:63], v[62:63], v[114:115]
	v_pk_mul_f32 v[58:59], v[58:59], v[118:119]
	v_pk_mul_f32 v[54:55], v[54:55], v[122:123]
	v_pk_mul_f32 v[50:51], v[50:51], v[126:127]
	v_pk_mul_f32 v[48:49], v[48:49], v[124:125]
	v_pk_mul_f32 v[44:45], v[44:45], v[112:113]
	v_pk_mul_f32 v[40:41], v[40:41], v[116:117]
	v_pk_mul_f32 v[36:37], v[36:37], v[120:121]
	v_pk_mul_f32 v[46:47], v[46:47], v[114:115]
	v_pk_mul_f32 v[42:43], v[42:43], v[118:119]
	v_pk_mul_f32 v[38:39], v[38:39], v[122:123]
	v_pk_mul_f32 v[34:35], v[34:35], v[126:127]
	v_pk_mul_f32 v[32:33], v[32:33], v[124:125]
	v_pk_mul_f32 v[28:29], v[28:29], v[112:113]
	v_pk_mul_f32 v[24:25], v[24:25], v[116:117]
	v_pk_mul_f32 v[20:21], v[20:21], v[120:121]
	v_pk_mul_f32 v[30:31], v[30:31], v[114:115]
	v_pk_mul_f32 v[26:27], v[26:27], v[118:119]
	v_pk_mul_f32 v[22:23], v[22:23], v[122:123]
	v_pk_mul_f32 v[18:19], v[18:19], v[126:127]
	v_pk_mul_f32 v[16:17], v[16:17], v[124:125]
.LBB0_219:
	s_waitcnt lgkmcnt(0)
	s_barrier
	ds_read_b128 v[64:67], v181 offset:32768
	ds_read_b128 v[68:71], v181 offset:40960
	v_add_f32_e32 v201, 0, v234
	v_add_f32_e32 v201, v235, v201
	v_add_f32_e32 v201, v236, v201
	s_waitcnt lgkmcnt(1)
	v_mfma_f32_32x32x16_bf16 v[80:95], v[64:67], v[108:111], 0
	v_add_f32_e32 v201, v237, v201
	v_add_f32_e32 v201, v238, v201
	ds_read_b128 v[204:207], v182 offset:32768
	ds_read_b128 v[208:211], v182 offset:40960
	v_add_f32_e32 v201, v239, v201
	v_add_f32_e32 v201, v240, v201
	v_add_f32_e32 v201, v241, v201
	v_add_f32_e32 v201, v242, v201
	s_waitcnt lgkmcnt(2)
	v_mfma_f32_32x32x16_bf16 v[64:79], v[68:71], v[108:111], 0
	v_add_f32_e32 v201, v243, v201
	v_add_f32_e32 v201, v244, v201
	v_add_f32_e32 v201, v245, v201
	v_add_f32_e32 v201, v246, v201
	v_add_f32_e32 v201, v247, v201
	v_add_f32_e32 v201, v252, v201
	v_add_f32_e32 v201, v253, v201
	s_waitcnt lgkmcnt(1)
	v_mfma_f32_32x32x16_bf16 v[80:95], v[204:207], v[104:107], v[80:95]
	v_add_f32_e32 v201, v218, v201
	v_add_f32_e32 v201, v219, v201
	v_add_f32_e32 v201, v220, v201
	v_add_f32_e32 v201, v221, v201
	v_add_f32_e32 v201, v222, v201
	v_add_f32_e32 v201, v223, v201
	v_add_f32_e32 v201, v224, v201
	s_waitcnt lgkmcnt(0)
	v_mfma_f32_32x32x16_bf16 v[64:79], v[208:211], v[104:107], v[64:79]
	ds_read_b128 v[204:207], v183 offset:32768
	ds_read_b128 v[208:211], v183 offset:40960
	v_add_f32_e32 v201, v225, v201
	v_add_f32_e32 v201, v226, v201
	v_add_f32_e32 v201, v227, v201
	v_add_f32_e32 v201, v228, v201
	v_add_f32_e32 v201, v229, v201
	v_add_f32_e32 v201, v230, v201
	s_waitcnt lgkmcnt(1)
	v_mfma_f32_32x32x16_bf16 v[80:95], v[204:207], v[100:103], v[80:95]
	v_add_f32_e32 v201, v231, v201
	v_add_f32_e32 v201, v232, v201
	v_add_f32_e32 v203, v233, v201
	s_waitcnt lgkmcnt(0)
	v_mfma_f32_32x32x16_bf16 v[64:79], v[208:211], v[100:103], v[64:79]
	ds_read_b128 v[204:207], v184 offset:32768
	ds_read_b128 v[208:211], v184 offset:40960
	v_cvt_pk_bf16_f32 v128, v234, v235
	v_cvt_pk_bf16_f32 v129, v236, v237
	v_cvt_pk_bf16_f32 v130, v238, v239
	v_cvt_pk_bf16_f32 v131, v240, v241
	v_cvt_pk_bf16_f32 v198, v242, v243
	v_cvt_pk_bf16_f32 v199, v244, v245
	s_waitcnt lgkmcnt(1)
	v_mfma_f32_32x32x16_bf16 v[80:95], v[204:207], v[96:99], v[80:95]
	v_mov_b32_e32 v204, v203
	s_nop 1
	v_permlane32_swap_b32_e32 v203, v204
	v_permlane32_swap_b32_e32 v128, v130
	v_permlane32_swap_b32_e32 v129, v131
	s_waitcnt lgkmcnt(0)
	v_mfma_f32_32x32x16_bf16 v[64:79], v[208:211], v[96:99], v[64:79]
	v_add_co_u32_e32 v116, vcc, s78, v152
	s_nop 1
	v_addc_co_u32_e32 v117, vcc, 0, v153, vcc
	v_add_co_u32_e32 v120, vcc, s78, v150
	s_nop 1
	v_addc_co_u32_e32 v121, vcc, 0, v151, vcc
	ds_read_b64_tr_b16 v[150:151], v179 offset:0
	ds_read_b64_tr_b16 v[152:153], v179 offset:0x800
	ds_read_b64_tr_b16 v[206:207], v179 offset:0x1000
	ds_read_b64_tr_b16 v[208:209], v179 offset:0x1800
	ds_read_b64_tr_b16 v[210:211], v179 offset:0x2000
	ds_read_b64_tr_b16 v[212:213], v179 offset:0x2800
	ds_read_b64_tr_b16 v[214:215], v179 offset:0x3000
	ds_read_b64_tr_b16 v[216:217], v179 offset:0x3800
	v_cvt_pk_bf16_f32 v200, v246, v247
	v_cvt_pk_bf16_f32 v201, v252, v253
	v_cvt_pk_bf16_f32 v190, v218, v219
	v_cvt_pk_bf16_f32 v191, v220, v221
	v_cvt_pk_bf16_f32 v192, v222, v223
	v_cvt_pk_bf16_f32 v193, v224, v225
	v_cvt_pk_bf16_f32 v194, v226, v227
	v_cvt_pk_bf16_f32 v195, v228, v229
	v_cvt_pk_bf16_f32 v196, v230, v231
	v_cvt_pk_bf16_f32 v197, v232, v233
	s_nop 0
	v_permlane32_swap_b32_e32 v198, v200
	v_permlane32_swap_b32_e32 v199, v201
	v_permlane32_swap_b32_e32 v190, v192
	v_permlane32_swap_b32_e32 v191, v193
	v_permlane32_swap_b32_e32 v194, v196
	v_permlane32_swap_b32_e32 v195, v197
	global_load_dwordx4 v[112:115], v[116:117], off offset:1024
	s_nop 0
	global_load_dwordx4 v[116:119], v[116:117], off
	s_nop 0
	global_load_dwordx4 v[124:127], v[120:121], off offset:1024
	s_nop 0
	global_load_dwordx4 v[120:123], v[120:121], off
	s_nop 0
	s_waitcnt lgkmcnt(6)
	v_mfma_f32_32x32x16_bf16 v[0:15], v[128:131], v[150:153], v[0:15]
	ds_read_b64_tr_b16 v[150:151], v179 offset:0x200
	ds_read_b64_tr_b16 v[152:153], v179 offset:0xa00
	v_max_f32_e32 v250, v80, v81
	v_max3_f32 v250, v250, v82, v83
	v_max3_f32 v250, v250, v84, v85
	v_max3_f32 v250, v250, v86, v87
	v_max3_f32 v250, v250, v88, v89
	v_max3_f32 v250, v250, v90, v91
	v_max3_f32 v250, v250, v92, v93
	s_waitcnt lgkmcnt(6)
	v_mfma_f32_32x32x16_bf16 v[0:15], v[198:201], v[206:209], v[0:15]
	ds_read_b64_tr_b16 v[206:207], v179 offset:0x1200
	ds_read_b64_tr_b16 v[208:209], v179 offset:0x1a00
	v_max3_f32 v250, v250, v94, v95
	v_max3_f32 v250, v250, v64, v65
	v_max3_f32 v250, v250, v66, v67
	v_max3_f32 v250, v250, v68, v69
	v_max3_f32 v250, v250, v70, v71
	v_max3_f32 v250, v250, v72, v73
	v_max3_f32 v250, v250, v74, v75
	v_max3_f32 v250, v250, v76, v77
	v_max3_f32 v250, v250, v78, v79
	s_waitcnt lgkmcnt(6)
	v_mfma_f32_32x32x16_bf16 v[0:15], v[190:193], v[210:213], v[0:15]
	ds_read_b64_tr_b16 v[210:211], v179 offset:0x2200
	ds_read_b64_tr_b16 v[212:213], v179 offset:0x2a00
	v_mov_b32_e32 v251, v250
	s_nop 1
	v_permlane32_swap_b32_e32 v250, v251
	v_max_f32_e32 v250, v250, v251
	v_sub_f32_e32 v251, v250, v186
	v_cmp_ge_f32_e32 vcc, s33, v251
	v_max_f32_e32 v251, v186, v186
	v_max_f32_e32 v251, v251, v250
	s_waitcnt lgkmcnt(6)
	v_mfma_f32_32x32x16_bf16 v[0:15], v[194:197], v[214:217], v[0:15]
	ds_read_b64_tr_b16 v[214:215], v179 offset:0x3200
	ds_read_b64_tr_b16 v[216:217], v179 offset:0x3a00
	v_sub_f32_e32 v250, v186, v251
	v_mul_f32_e32 v250, 0x3e38aa3b, v250
	v_exp_f32_e32 v250, v250
	s_cmp_eq_u64 vcc, exec
	s_cselect_b64 s[6:7], -1, 0
	v_cndmask_b32_e64 v186, v251, v186, s[6:7]
	v_mul_f32_e32 v254, 0xbe38aa3b, v186
	s_waitcnt lgkmcnt(6)
	v_mfma_f32_32x32x16_bf16 v[48:63], v[128:131], v[150:153], v[48:63]
	ds_read_b64_tr_b16 v[150:151], v179 offset:0x400
	ds_read_b64_tr_b16 v[152:153], v179 offset:0xc00
	v_fmamk_f32 v80, v80, 0x3e38aa3b, v254
	v_fmamk_f32 v81, v81, 0x3e38aa3b, v254
	v_fmamk_f32 v64, v64, 0x3e38aa3b, v254
	v_fmamk_f32 v65, v65, 0x3e38aa3b, v254
	v_exp_f32_e32 v234, v80
	v_exp_f32_e32 v235, v81
	v_fmamk_f32 v82, v82, 0x3e38aa3b, v254
	v_fmamk_f32 v83, v83, 0x3e38aa3b, v254
	s_waitcnt lgkmcnt(6)
	v_mfma_f32_32x32x16_bf16 v[48:63], v[198:201], v[206:209], v[48:63]
	ds_read_b64_tr_b16 v[206:207], v179 offset:0x1400
	ds_read_b64_tr_b16 v[208:209], v179 offset:0x1c00
	v_exp_f32_e32 v218, v64
	v_exp_f32_e32 v219, v65
	v_fmamk_f32 v66, v66, 0x3e38aa3b, v254
	v_fmamk_f32 v67, v67, 0x3e38aa3b, v254
	v_exp_f32_e32 v236, v82
	s_waitcnt lgkmcnt(6)
	v_mfma_f32_32x32x16_bf16 v[48:63], v[190:193], v[210:213], v[48:63]
	ds_read_b64_tr_b16 v[210:211], v179 offset:0x2400
	ds_read_b64_tr_b16 v[212:213], v179 offset:0x2c00
	v_exp_f32_e32 v237, v83
	v_fmamk_f32 v84, v84, 0x3e38aa3b, v254
	v_fmamk_f32 v85, v85, 0x3e38aa3b, v254
	v_exp_f32_e32 v220, v66
	v_exp_f32_e32 v221, v67
	s_waitcnt lgkmcnt(6)
	v_mfma_f32_32x32x16_bf16 v[48:63], v[194:197], v[214:217], v[48:63]
	ds_read_b64_tr_b16 v[214:215], v179 offset:0x3400
	ds_read_b64_tr_b16 v[216:217], v179 offset:0x3c00
	v_fmamk_f32 v68, v68, 0x3e38aa3b, v254
	v_fmamk_f32 v69, v69, 0x3e38aa3b, v254
	v_exp_f32_e32 v238, v84
	v_exp_f32_e32 v239, v85
	v_fmamk_f32 v86, v86, 0x3e38aa3b, v254
	v_fmamk_f32 v87, v87, 0x3e38aa3b, v254
	s_waitcnt lgkmcnt(6)
	v_mfma_f32_32x32x16_bf16 v[32:47], v[128:131], v[150:153], v[32:47]
	ds_read_b64_tr_b16 v[150:151], v179 offset:0x600
	ds_read_b64_tr_b16 v[152:153], v179 offset:0xe00
	v_exp_f32_e32 v222, v68
	v_exp_f32_e32 v223, v69
	v_fmamk_f32 v70, v70, 0x3e38aa3b, v254
	v_fmamk_f32 v71, v71, 0x3e38aa3b, v254
	v_exp_f32_e32 v240, v86
	s_waitcnt lgkmcnt(6)
	v_mfma_f32_32x32x16_bf16 v[32:47], v[198:201], v[206:209], v[32:47]
	ds_read_b64_tr_b16 v[206:207], v179 offset:0x1600
	ds_read_b64_tr_b16 v[208:209], v179 offset:0x1e00
	v_exp_f32_e32 v241, v87
	v_fmamk_f32 v88, v88, 0x3e38aa3b, v254
	v_fmamk_f32 v89, v89, 0x3e38aa3b, v254
	v_exp_f32_e32 v224, v70
	v_exp_f32_e32 v225, v71
	s_waitcnt lgkmcnt(6)
	v_mfma_f32_32x32x16_bf16 v[32:47], v[190:193], v[210:213], v[32:47]
	ds_read_b64_tr_b16 v[210:211], v179 offset:0x2600
	ds_read_b64_tr_b16 v[212:213], v179 offset:0x2e00
	v_fmamk_f32 v72, v72, 0x3e38aa3b, v254
	v_fmamk_f32 v73, v73, 0x3e38aa3b, v254
	v_exp_f32_e32 v242, v88
	v_exp_f32_e32 v243, v89
	v_fmamk_f32 v90, v90, 0x3e38aa3b, v254
	v_fmamk_f32 v91, v91, 0x3e38aa3b, v254
	s_waitcnt lgkmcnt(6)
	v_mfma_f32_32x32x16_bf16 v[32:47], v[194:197], v[214:217], v[32:47]
	ds_read_b64_tr_b16 v[214:215], v179 offset:0x3600
	ds_read_b64_tr_b16 v[216:217], v179 offset:0x3e00
	v_exp_f32_e32 v226, v72
	v_exp_f32_e32 v227, v73
	v_fmamk_f32 v74, v74, 0x3e38aa3b, v254
	v_fmamk_f32 v75, v75, 0x3e38aa3b, v254
	v_exp_f32_e32 v244, v90
	s_waitcnt lgkmcnt(6)
	v_mfma_f32_32x32x16_bf16 v[16:31], v[128:131], v[150:153], v[16:31]
	v_exp_f32_e32 v245, v91
	v_fmamk_f32 v92, v92, 0x3e38aa3b, v254
	v_fmamk_f32 v93, v93, 0x3e38aa3b, v254
	v_exp_f32_e32 v228, v74
	v_exp_f32_e32 v229, v75
	s_waitcnt lgkmcnt(4)
	v_mfma_f32_32x32x16_bf16 v[16:31], v[198:201], v[206:209], v[16:31]
	v_fmamk_f32 v76, v76, 0x3e38aa3b, v254
	v_fmamk_f32 v77, v77, 0x3e38aa3b, v254
	v_exp_f32_e32 v246, v92
	v_exp_f32_e32 v247, v93
	v_fmamk_f32 v94, v94, 0x3e38aa3b, v254
	v_fmamk_f32 v95, v95, 0x3e38aa3b, v254
	s_waitcnt lgkmcnt(2)
	v_mfma_f32_32x32x16_bf16 v[16:31], v[190:193], v[210:213], v[16:31]
	v_exp_f32_e32 v230, v76
	v_exp_f32_e32 v231, v77
	v_fmamk_f32 v78, v78, 0x3e38aa3b, v254
	v_fmamk_f32 v79, v79, 0x3e38aa3b, v254
	v_exp_f32_e32 v252, v94
	s_waitcnt lgkmcnt(0)
	v_mfma_f32_32x32x16_bf16 v[16:31], v[194:197], v[214:217], v[16:31]
	v_exp_f32_e32 v253, v95
	s_nop 0
	v_exp_f32_e32 v232, v78
	v_exp_f32_e32 v233, v79
	s_barrier
	s_waitcnt vmcnt(0)
	v_cndmask_b32_e64 v128, v250, 1.0, s[6:7]
	v_cmp_gt_f32_e32 vcc, 1.0, v128
	s_waitcnt vmcnt(3)
	ds_write_b128 v134, v[112:115] offset:16384
	s_waitcnt vmcnt(1)
	ds_write_b128 v145, v[124:127] offset:16384
	ds_write_b128 v175, v[116:119] offset:49152
	s_waitcnt vmcnt(0)
	ds_write_b128 v180, v[120:123] offset:49152
	s_cbranch_vccz .LBB0_223
	s_and_saveexec_b64 s[60:61], s[4:5]
	ds_write_b32 v176, v128 offset:128
	s_or_b64 exec, exec, s[60:61]
	s_waitcnt lgkmcnt(0)
	v_add_u32_e32 v124, v174, v144
	ds_read_b128 v[112:115], v124 offset:224
	ds_read_b128 v[116:119], v124 offset:192
	ds_read_b128 v[120:123], v124 offset:160
	ds_read_b128 v[124:127], v124 offset:128
	s_waitcnt lgkmcnt(3)
	v_pk_mul_f32 v[12:13], v[12:13], v[112:113]
	s_waitcnt lgkmcnt(2)
	v_pk_mul_f32 v[8:9], v[8:9], v[116:117]
	s_waitcnt lgkmcnt(1)
	v_pk_mul_f32 v[4:5], v[4:5], v[120:121]
	v_pk_mul_f32 v[14:15], v[14:15], v[114:115]
	v_pk_mul_f32 v[10:11], v[10:11], v[118:119]
	v_pk_mul_f32 v[6:7], v[6:7], v[122:123]
	s_waitcnt lgkmcnt(0)
	v_pk_mul_f32 v[2:3], v[2:3], v[126:127]
	v_pk_mul_f32 v[0:1], v[0:1], v[124:125]
	v_pk_mul_f32 v[60:61], v[60:61], v[112:113]
	v_pk_mul_f32 v[56:57], v[56:57], v[116:117]
	v_pk_mul_f32 v[52:53], v[52:53], v[120:121]
	v_pk_mul_f32 v[62:63], v[62:63], v[114:115]
	v_pk_mul_f32 v[58:59], v[58:59], v[118:119]
	v_pk_mul_f32 v[54:55], v[54:55], v[122:123]
	v_pk_mul_f32 v[50:51], v[50:51], v[126:127]
	v_pk_mul_f32 v[48:49], v[48:49], v[124:125]
	v_pk_mul_f32 v[44:45], v[44:45], v[112:113]
	v_pk_mul_f32 v[40:41], v[40:41], v[116:117]
	v_pk_mul_f32 v[36:37], v[36:37], v[120:121]
	v_pk_mul_f32 v[46:47], v[46:47], v[114:115]
	v_pk_mul_f32 v[42:43], v[42:43], v[118:119]
	v_pk_mul_f32 v[38:39], v[38:39], v[122:123]
	v_pk_mul_f32 v[34:35], v[34:35], v[126:127]
	v_pk_mul_f32 v[32:33], v[32:33], v[124:125]
	v_pk_mul_f32 v[28:29], v[28:29], v[112:113]
	v_pk_mul_f32 v[24:25], v[24:25], v[116:117]
	v_pk_mul_f32 v[20:21], v[20:21], v[120:121]
	v_pk_mul_f32 v[30:31], v[30:31], v[114:115]
	v_pk_mul_f32 v[26:27], v[26:27], v[118:119]
	v_pk_mul_f32 v[22:23], v[22:23], v[122:123]
	v_pk_mul_f32 v[18:19], v[18:19], v[126:127]
	v_pk_mul_f32 v[16:17], v[16:17], v[124:125]
